# out-proj: next-tile first 8 LDS-DMA loads issued before the current tile's epilogue (same as in-proj)
# baseline (speedup 1.0000x reference)
; DI u16 f2bf(float x) { unsigned u = __float_as_uint(x); u += 0x7fffu + ((u >> 16) & 1u); return (u16)(u >> 16); }
; DI void gemm8p(const u16* __restrict__ A, const u16* __restrict__ Bt, int brow, int bcol, f32x4 (&acc)[2][2][4][2]) {
;   constexpr int K = 1024, BK = 64, HALF = 128, HT = HALF * BK;
;   u16* shm = (u16*)lds_dyn;
;     ...
;   int tid8 = threadIdx.x; asm volatile("" : "+v"(tid8));
;   const int wid = tid8 >> 6, lane = tid8 & 63, wr = wid >> 2, wc = wid & 3, fr = lane & 15, fq = lane >> 4;
;   int soff0, soff1;
;   { int r_, c_; g8_stage_rc(tid8 * 16, r_, c_); soff0 = r_ * K + c_; g8_stage_rc(tid8 * 16 + 8192, r_, c_); soff1 = r_ * K + c_; }
;   bf16x8 At[4][2], B0[2][2], B1[2][2];
;   constexpr int nt = K / BK;
;   __syncthreads();
;   G8_STAGE(G8_SB(0, 0), Bt, bcol, 0); G8_STAGE(G8_SA(0, 0), A, brow, 0);
;   G8_STAGE(G8_SB(0, 1), Bt, bcol + HALF, 0); G8_STAGE(G8_SA(0, 1), A, brow + HALF, 0);
; DI void phase_outproj(const Params& p, int layer, char* lds) {
;     ...
;     u16* yo = (u16*)(p.ws + OFF_XB) + base;
; #pragma unroll
;     for (int ai = 0; ai < 2; ++ai)
; #pragma unroll
;       for (int bj = 0; bj < 2; ++bj)
; #pragma unroll
;         for (int m = 0; m < 4; ++m) {
; #pragma unroll
;           for (int n = 0; n < 2; ++n)
; #pragma unroll
;             for (int j = 0; j < 4; ++j) yo[(ai * 128 + m * 16 + j) * DM + bj * 128 + n * 16] = f2bf(acc[ai][bj][m][n][j]);
.LBB0_519:
	s_or_b64 exec, exec, s[4:5]
	v_readlane_b32 s4, v254, 55
	v_readlane_b32 s5, v254, 56
	s_waitcnt vmcnt(0)
	v_mov_b32_e32 v0, v184
	s_andn2_b64 vcc, exec, s[4:5]
	s_barrier
	s_cbranch_vccnz .LBB0_528
	s_lshl_b64 s[4:5], s[80:81], 21
	v_readlane_b32 s6, v254, 20
	s_add_u32 s20, s6, s4
	v_readlane_b32 s4, v254, 21
	v_lshrrev_b32_e32 v3, 2, v0
	s_addc_u32 s21, s4, s5
	v_and_b32_e32 v1, 15, v0
	v_ashrrev_i32_e32 v2, 2, v0
	v_and_b32_e32 v3, 12, v3
	s_movk_i32 s4, 0xffc0
	v_lshrrev_b32_e32 v0, 1, v0
	v_and_or_b32 v4, v2, s4, v3
	v_and_or_b32 v142, v0, s61, v1
	v_readlane_b32 s23, v254, 53
	s_mov_b32 s32, 0
	s_branch .LBB0_522
.LBB0_521:
	s_or_b64 exec, exec, s[8:9]
	s_mov_b32 s32, 0
	s_add_i32 s7, s23, s63
	v_readlane_b32 s12, v254, 54
	v_lshlrev_b32_e32 v150, 4, v184
	s_cmp_lt_i32 s7, s12
	s_cbranch_scc0 .Lopf_none
	s_mov_b32 s32, 1
	s_lshr_b32 s12, s7, 2
	s_and_b32 s13, s7, 3
	s_lshl_b32 s13, s13, 19
	s_lshl_b32 s24, s12, 3
	s_or_b32 s24, s24, s28
	v_readlane_b32 s10, v254, 30
	v_readlane_b32 s11, v254, 31
	v_lshrrev_b32_e32 v151, 10, v150
	v_and_b32_e32 v152, 0x3ff, v150
	s_and_b64 s[10:11], s[10:11], exec
	s_cselect_b32 s24, s24, s12
	s_lshl_b32 s24, s24, 19
	s_add_u32 s10, s20, s13
	s_addc_u32 s11, s21, 0
	v_readlane_b32 s26, v254, 49
	v_readlane_b32 s27, v254, 50
	v_lshrrev_b32_e32 v153, 4, v152
	v_and_b32_e32 v153, 32, v153
	s_add_u32 s12, s26, s24
	s_addc_u32 s13, s27, 0
	v_xor_b32_e32 v152, v152, v153
	v_lshrrev_b32_e32 v153, 1, v151
	v_lshlrev_b32_e32 v153, 4, v153
	v_lshrrev_b32_e32 v154, 6, v152
	v_add_u32_e32 v153, v153, v154
	v_and_b32_e32 v154, 1, v151
	v_lshlrev_b32_e32 v154, 5, v154
	v_bfe_u32 v155, v152, 1, 5
	v_add_u32_e32 v154, v154, v155
	v_lshl_add_u32 v153, v153, 10, v154
	v_lshlrev_b32_e32 v156, 1, v153
	v_mov_b32_e32 v157, 0
	v_add_u32_e32 v158, 0x20000, v156
	v_mov_b32_e32 v159, 0
	v_readfirstlane_b32 s25, v150
	v_readlane_b32 s26, v255, 7
	v_readlane_b32 s27, v255, 8
	v_lshl_add_u64 v[160:161], s[10:11], 0, v[156:157]
	v_lshl_add_u64 v[162:163], s[10:11], 0, v[158:159]
	v_lshl_add_u64 v[164:165], s[12:13], 0, v[156:157]
	v_lshl_add_u64 v[166:167], s[12:13], 0, v[158:159]
	s_add_u32 s10, s10, 0x40000
	s_addc_u32 s11, s11, 0
	s_add_u32 s12, s12, 0x40000
	s_addc_u32 s13, s13, 0
	v_lshl_add_u64 v[168:169], s[10:11], 0, v[156:157]
	v_lshl_add_u64 v[170:171], s[10:11], 0, v[158:159]
	v_lshl_add_u64 v[172:173], s[12:13], 0, v[156:157]
	v_lshl_add_u64 v[174:175], s[12:13], 0, v[158:159]
	s_add_u32 s7, s26, s25
	s_mov_b32 m0, s7
	s_nop 0
	global_load_lds_dwordx4 v[160:161], off
	s_add_u32 s7, s7, 0x2000
	s_mov_b32 m0, s7
	s_nop 0
	global_load_lds_dwordx4 v[162:163], off
	s_mov_b32 m0, s25
	s_nop 0
	global_load_lds_dwordx4 v[164:165], off
	s_add_u32 s7, s25, 0x2000
	s_mov_b32 m0, s7
	s_nop 0
	global_load_lds_dwordx4 v[166:167], off
	s_add_u32 s7, s27, s25
	s_mov_b32 m0, s7
	s_nop 0
	global_load_lds_dwordx4 v[168:169], off
	s_add_u32 s7, s7, 0x2000
	s_mov_b32 m0, s7
	s_nop 0
	global_load_lds_dwordx4 v[170:171], off
	s_add_u32 s7, s25, 0x4000
	s_mov_b32 m0, s7
	s_nop 0
	global_load_lds_dwordx4 v[172:173], off
	s_add_u32 s7, s25, 0x6000
	s_mov_b32 m0, s7
	s_nop 0
	global_load_lds_dwordx4 v[174:175], off
.Lopf_none:
	v_add_u32_e32 v130, s6, v4
	v_ashrrev_i32_e32 v131, 31, v130
	v_or_b32_e32 v132, s4, v142
	v_lshlrev_b64 v[130:131], 11, v[130:131]
	v_ashrrev_i32_e32 v133, 31, v132
	v_lshl_add_u64 v[130:131], s[78:79], 0, v[130:131]
	v_lshl_add_u64 v[130:131], v[132:133], 1, v[130:131]
	v_bfe_u32 v132, v126, 16, 1
	v_add3_u32 v126, v126, v132, s45
	global_store_short_d16_hi v[130:131], v126, off
	v_bfe_u32 v126, v127, 16, 1
	v_add3_u32 v126, v127, v126, s45
	global_store_short_d16_hi v[130:131], v126, off offset:2048
	v_bfe_u32 v126, v128, 16, 1
	v_add3_u32 v128, v128, v126, s45
	v_add_co_u32_e32 v126, vcc, s48, v130
	s_nop 1
	v_addc_co_u32_e32 v127, vcc, 0, v131, vcc
	global_store_short_d16_hi v[126:127], v128, off
	v_bfe_u32 v128, v129, 16, 1
	v_add3_u32 v128, v129, v128, s45
	global_store_short_d16_hi v[126:127], v128, off offset:2048
	v_bfe_u32 v128, v122, 16, 1
	v_add3_u32 v122, v122, v128, s45
	global_store_short_d16_hi v[130:131], v122, off offset:32
	v_bfe_u32 v122, v123, 16, 1
	v_add3_u32 v122, v123, v122, s45
	global_store_short_d16_hi v[130:131], v122, off offset:2080
	v_bfe_u32 v122, v124, 16, 1
	v_add3_u32 v122, v124, v122, s45
	global_store_short_d16_hi v[126:127], v122, off offset:32
	v_bfe_u32 v122, v125, 16, 1
	v_add3_u32 v122, v125, v122, s45
	global_store_short_d16_hi v[126:127], v122, off offset:2080
	v_bfe_u32 v122, v118, 16, 1
	s_mov_b32 s4, 0x8000
	v_add3_u32 v118, v118, v122, s45
	v_add_co_u32_e32 v122, vcc, s4, v130
	s_mov_b32 s4, 0x9000
	s_nop 0
	v_addc_co_u32_e32 v123, vcc, 0, v131, vcc
	v_add_co_u32_e32 v124, vcc, s4, v130
	s_nop 1
	v_addc_co_u32_e32 v125, vcc, 0, v131, vcc
	global_store_short_d16_hi v[124:125], v118, off offset:-4096
	v_bfe_u32 v118, v119, 16, 1
	v_add3_u32 v118, v119, v118, s45
	global_store_short_d16_hi v[122:123], v118, off offset:2048
	v_bfe_u32 v118, v120, 16, 1
	v_add3_u32 v118, v120, v118, s45
	global_store_short_d16_hi v[124:125], v118, off
	v_bfe_u32 v118, v121, 16, 1
	v_add3_u32 v118, v121, v118, s45
	global_store_short_d16_hi v[124:125], v118, off offset:2048
	v_bfe_u32 v118, v114, 16, 1
	v_add3_u32 v114, v114, v118, s45
	global_store_short_d16_hi v[122:123], v114, off offset:32
	v_bfe_u32 v114, v115, 16, 1
	v_add3_u32 v114, v115, v114, s45
	global_store_short_d16_hi v[122:123], v114, off offset:2080
	v_bfe_u32 v114, v116, 16, 1
	v_add3_u32 v114, v116, v114, s45
	global_store_short_d16_hi v[124:125], v114, off offset:32
	v_bfe_u32 v114, v117, 16, 1
; DI u16 f2bf(float x) { unsigned u = __float_as_uint(x); u += 0x7fffu + ((u >> 16) & 1u); return (u16)(u >> 16); }
; DI void phase_outproj(const Params& p, int layer, char* lds) {
;     ...
;     u16* yo = (u16*)(p.ws + OFF_XB) + base;
; #pragma unroll
;     for (int ai = 0; ai < 2; ++ai)
; #pragma unroll
;       for (int bj = 0; bj < 2; ++bj)
; #pragma unroll
;         for (int m = 0; m < 4; ++m) {
; #pragma unroll
;           for (int n = 0; n < 2; ++n)
; #pragma unroll
;             for (int j = 0; j < 4; ++j) yo[(ai * 128 + m * 16 + j) * DM + bj * 128 + n * 16] = f2bf(acc[ai][bj][m][n][j]);
;           __builtin_amdgcn_sched_barrier(0);
	v_add3_u32 v114, v117, v114, s45
	global_store_short_d16_hi v[124:125], v114, off offset:2080
	v_bfe_u32 v114, v110, 16, 1
	s_mov_b32 s4, 0x10000
	v_add3_u32 v110, v110, v114, s45
	v_add_co_u32_e32 v114, vcc, s4, v130
	s_mov_b32 s4, 0x11000
	s_nop 0
	v_addc_co_u32_e32 v115, vcc, 0, v131, vcc
	v_add_co_u32_e32 v116, vcc, s4, v130
	s_nop 1
	v_addc_co_u32_e32 v117, vcc, 0, v131, vcc
	global_store_short_d16_hi v[116:117], v110, off offset:-4096
	v_bfe_u32 v110, v111, 16, 1
	v_add3_u32 v110, v111, v110, s45
	global_store_short_d16_hi v[114:115], v110, off offset:2048
	v_bfe_u32 v110, v112, 16, 1
	v_add3_u32 v110, v112, v110, s45
	global_store_short_d16_hi v[116:117], v110, off
	v_bfe_u32 v110, v113, 16, 1
	v_add3_u32 v110, v113, v110, s45
	global_store_short_d16_hi v[116:117], v110, off offset:2048
	v_bfe_u32 v110, v106, 16, 1
	v_add3_u32 v106, v106, v110, s45
	global_store_short_d16_hi v[114:115], v106, off offset:32
	v_bfe_u32 v106, v107, 16, 1
	v_add3_u32 v106, v107, v106, s45
	global_store_short_d16_hi v[114:115], v106, off offset:2080
	v_bfe_u32 v106, v108, 16, 1
	v_add3_u32 v106, v108, v106, s45
	global_store_short_d16_hi v[116:117], v106, off offset:32
	v_bfe_u32 v106, v109, 16, 1
	v_add3_u32 v106, v109, v106, s45
	global_store_short_d16_hi v[116:117], v106, off offset:2080
	v_bfe_u32 v106, v102, 16, 1
	s_mov_b32 s4, 0x18000
	v_add3_u32 v102, v102, v106, s45
	v_add_co_u32_e32 v106, vcc, s4, v130
	s_mov_b32 s4, 0x19000
	s_nop 0
	v_addc_co_u32_e32 v107, vcc, 0, v131, vcc
	v_add_co_u32_e32 v108, vcc, s4, v130
	s_nop 1
	v_addc_co_u32_e32 v109, vcc, 0, v131, vcc
	global_store_short_d16_hi v[108:109], v102, off offset:-4096
	v_bfe_u32 v102, v103, 16, 1
	v_add3_u32 v102, v103, v102, s45
	global_store_short_d16_hi v[106:107], v102, off offset:2048
	v_bfe_u32 v102, v104, 16, 1
	v_add3_u32 v102, v104, v102, s45
	global_store_short_d16_hi v[108:109], v102, off
	v_bfe_u32 v102, v105, 16, 1
	v_add3_u32 v102, v105, v102, s45
	global_store_short_d16_hi v[108:109], v102, off offset:2048
	v_bfe_u32 v102, v98, 16, 1
	v_add3_u32 v98, v98, v102, s45
	global_store_short_d16_hi v[106:107], v98, off offset:32
	v_bfe_u32 v98, v99, 16, 1
	v_add3_u32 v98, v99, v98, s45
	global_store_short_d16_hi v[106:107], v98, off offset:2080
	v_bfe_u32 v98, v100, 16, 1
	v_add3_u32 v98, v100, v98, s45
	global_store_short_d16_hi v[108:109], v98, off offset:32
	v_bfe_u32 v98, v101, 16, 1
	v_add3_u32 v98, v101, v98, s45
	global_store_short_d16_hi v[108:109], v98, off offset:2080
	v_bfe_u32 v98, v94, 16, 1
	v_add3_u32 v94, v94, v98, s45
	global_store_short_d16_hi v[130:131], v94, off offset:256
	v_bfe_u32 v94, v95, 16, 1
	v_add3_u32 v94, v95, v94, s45
	global_store_short_d16_hi v[130:131], v94, off offset:2304
	v_bfe_u32 v94, v96, 16, 1
	v_add3_u32 v94, v96, v94, s45
	global_store_short_d16_hi v[126:127], v94, off offset:256
	v_bfe_u32 v94, v97, 16, 1
	v_add3_u32 v94, v97, v94, s45
	global_store_short_d16_hi v[126:127], v94, off offset:2304
	v_bfe_u32 v94, v90, 16, 1
	v_add3_u32 v90, v90, v94, s45
	global_store_short_d16_hi v[130:131], v90, off offset:288
	v_bfe_u32 v90, v91, 16, 1
	v_add3_u32 v90, v91, v90, s45
	global_store_short_d16_hi v[130:131], v90, off offset:2336
	v_bfe_u32 v90, v92, 16, 1
	v_add3_u32 v90, v92, v90, s45
	global_store_short_d16_hi v[126:127], v90, off offset:288
	v_bfe_u32 v90, v93, 16, 1
	v_add3_u32 v90, v93, v90, s45
	global_store_short_d16_hi v[126:127], v90, off offset:2336
	v_bfe_u32 v90, v86, 16, 1
	v_add3_u32 v86, v86, v90, s45
	global_store_short_d16_hi v[122:123], v86, off offset:256
	v_bfe_u32 v86, v87, 16, 1
	v_add3_u32 v86, v87, v86, s45
	global_store_short_d16_hi v[122:123], v86, off offset:2304
	v_bfe_u32 v86, v88, 16, 1
	v_add3_u32 v86, v88, v86, s45
	global_store_short_d16_hi v[124:125], v86, off offset:256
	v_bfe_u32 v86, v89, 16, 1
	v_add3_u32 v86, v89, v86, s45
	global_store_short_d16_hi v[124:125], v86, off offset:2304
	v_bfe_u32 v86, v82, 16, 1
	v_add3_u32 v82, v82, v86, s45
	global_store_short_d16_hi v[122:123], v82, off offset:288
	v_bfe_u32 v82, v83, 16, 1
	v_add3_u32 v82, v83, v82, s45
	global_store_short_d16_hi v[122:123], v82, off offset:2336
	v_bfe_u32 v82, v84, 16, 1
	v_add3_u32 v82, v84, v82, s45
	global_store_short_d16_hi v[124:125], v82, off offset:288
	v_bfe_u32 v82, v85, 16, 1
	v_add3_u32 v82, v85, v82, s45
	global_store_short_d16_hi v[124:125], v82, off offset:2336
	v_bfe_u32 v82, v78, 16, 1
	v_add3_u32 v78, v78, v82, s45
	global_store_short_d16_hi v[114:115], v78, off offset:256
	v_bfe_u32 v78, v79, 16, 1
	v_add3_u32 v78, v79, v78, s45
	global_store_short_d16_hi v[114:115], v78, off offset:2304
	v_bfe_u32 v78, v80, 16, 1
	v_add3_u32 v78, v80, v78, s45
	global_store_short_d16_hi v[116:117], v78, off offset:256
	v_bfe_u32 v78, v81, 16, 1
	v_add3_u32 v78, v81, v78, s45
	global_store_short_d16_hi v[116:117], v78, off offset:2304
	v_bfe_u32 v78, v74, 16, 1
	v_add3_u32 v74, v74, v78, s45
	global_store_short_d16_hi v[114:115], v74, off offset:288
	v_bfe_u32 v74, v75, 16, 1
	v_add3_u32 v74, v75, v74, s45
	global_store_short_d16_hi v[114:115], v74, off offset:2336
	v_bfe_u32 v74, v76, 16, 1
	v_add3_u32 v74, v76, v74, s45
	global_store_short_d16_hi v[116:117], v74, off offset:288
	v_bfe_u32 v74, v77, 16, 1
	v_add3_u32 v74, v77, v74, s45
	global_store_short_d16_hi v[116:117], v74, off offset:2336
	v_bfe_u32 v74, v70, 16, 1
	v_add3_u32 v70, v70, v74, s45
	global_store_short_d16_hi v[106:107], v70, off offset:256
	v_bfe_u32 v70, v71, 16, 1
	v_add3_u32 v70, v71, v70, s45
	global_store_short_d16_hi v[106:107], v70, off offset:2304
	v_bfe_u32 v70, v72, 16, 1
	v_add3_u32 v70, v72, v70, s45
	global_store_short_d16_hi v[108:109], v70, off offset:256
; DI u16 f2bf(float x) { unsigned u = __float_as_uint(x); u += 0x7fffu + ((u >> 16) & 1u); return (u16)(u >> 16); }
; DI void phase_outproj(const Params& p, int layer, char* lds) {
;     ...
;     u16* yo = (u16*)(p.ws + OFF_XB) + base;
; #pragma unroll
;     for (int ai = 0; ai < 2; ++ai)
; #pragma unroll
;       for (int bj = 0; bj < 2; ++bj)
; #pragma unroll
;         for (int m = 0; m < 4; ++m) {
; #pragma unroll
;           for (int n = 0; n < 2; ++n)
; #pragma unroll
;             for (int j = 0; j < 4; ++j) yo[(ai * 128 + m * 16 + j) * DM + bj * 128 + n * 16] = f2bf(acc[ai][bj][m][n][j]);
;           __builtin_amdgcn_sched_barrier(0);
	v_bfe_u32 v70, v73, 16, 1
	v_add3_u32 v70, v73, v70, s45
	global_store_short_d16_hi v[108:109], v70, off offset:2304
	v_bfe_u32 v70, v66, 16, 1
	v_add3_u32 v66, v66, v70, s45
	global_store_short_d16_hi v[106:107], v66, off offset:288
	v_bfe_u32 v66, v67, 16, 1
	v_add3_u32 v66, v67, v66, s45
	global_store_short_d16_hi v[106:107], v66, off offset:2336
	v_bfe_u32 v66, v68, 16, 1
	v_add3_u32 v66, v68, v66, s45
	global_store_short_d16_hi v[108:109], v66, off offset:288
	v_bfe_u32 v66, v69, 16, 1
	v_add3_u32 v66, v69, v66, s45
	global_store_short_d16_hi v[108:109], v66, off offset:2336
	v_bfe_u32 v66, v62, 16, 1
	s_mov_b32 s4, 0x40000
	v_add3_u32 v62, v62, v66, s45
	v_add_co_u32_e32 v66, vcc, s4, v130
	s_mov_b32 s4, 0x41000
	s_nop 0
	v_addc_co_u32_e32 v67, vcc, 0, v131, vcc
	v_add_co_u32_e32 v68, vcc, s4, v130
	s_nop 1
	v_addc_co_u32_e32 v69, vcc, 0, v131, vcc
	global_store_short_d16_hi v[68:69], v62, off offset:-4096
	v_bfe_u32 v62, v63, 16, 1
	v_add3_u32 v62, v63, v62, s45
	global_store_short_d16_hi v[66:67], v62, off offset:2048
	v_bfe_u32 v62, v64, 16, 1
	v_add3_u32 v62, v64, v62, s45
	global_store_short_d16_hi v[68:69], v62, off
	v_bfe_u32 v62, v65, 16, 1
	v_add3_u32 v62, v65, v62, s45
	global_store_short_d16_hi v[68:69], v62, off offset:2048
	v_bfe_u32 v62, v58, 16, 1
	v_add3_u32 v58, v58, v62, s45
	global_store_short_d16_hi v[66:67], v58, off offset:32
	v_bfe_u32 v58, v59, 16, 1
	v_add3_u32 v58, v59, v58, s45
	global_store_short_d16_hi v[66:67], v58, off offset:2080
	v_bfe_u32 v58, v60, 16, 1
	v_add3_u32 v58, v60, v58, s45
	global_store_short_d16_hi v[68:69], v58, off offset:32
	v_bfe_u32 v58, v61, 16, 1
	v_add3_u32 v58, v61, v58, s45
	global_store_short_d16_hi v[68:69], v58, off offset:2080
	v_bfe_u32 v58, v54, 16, 1
	s_mov_b32 s4, 0x48000
	v_add3_u32 v54, v54, v58, s45
	v_add_co_u32_e32 v58, vcc, s4, v130
	s_mov_b32 s4, 0x49000
	s_nop 0
	v_addc_co_u32_e32 v59, vcc, 0, v131, vcc
	v_add_co_u32_e32 v60, vcc, s4, v130
	s_nop 1
	v_addc_co_u32_e32 v61, vcc, 0, v131, vcc
	global_store_short_d16_hi v[60:61], v54, off offset:-4096
	v_bfe_u32 v54, v55, 16, 1
	v_add3_u32 v54, v55, v54, s45
	global_store_short_d16_hi v[58:59], v54, off offset:2048
	v_bfe_u32 v54, v56, 16, 1
	v_add3_u32 v54, v56, v54, s45
	global_store_short_d16_hi v[60:61], v54, off
	v_bfe_u32 v54, v57, 16, 1
	v_add3_u32 v54, v57, v54, s45
	global_store_short_d16_hi v[60:61], v54, off offset:2048
	v_bfe_u32 v54, v50, 16, 1
	v_add3_u32 v50, v50, v54, s45
	global_store_short_d16_hi v[58:59], v50, off offset:32
	v_bfe_u32 v50, v51, 16, 1
	v_add3_u32 v50, v51, v50, s45
	global_store_short_d16_hi v[58:59], v50, off offset:2080
	v_bfe_u32 v50, v52, 16, 1
	v_add3_u32 v50, v52, v50, s45
	global_store_short_d16_hi v[60:61], v50, off offset:32
	v_bfe_u32 v50, v53, 16, 1
	v_add3_u32 v50, v53, v50, s45
	global_store_short_d16_hi v[60:61], v50, off offset:2080
	v_bfe_u32 v50, v46, 16, 1
	s_mov_b32 s4, 0x50000
	v_add3_u32 v46, v46, v50, s45
	v_add_co_u32_e32 v50, vcc, s4, v130
	s_mov_b32 s4, 0x51000
	s_nop 0
	v_addc_co_u32_e32 v51, vcc, 0, v131, vcc
	v_add_co_u32_e32 v52, vcc, s4, v130
	s_nop 1
	v_addc_co_u32_e32 v53, vcc, 0, v131, vcc
	global_store_short_d16_hi v[52:53], v46, off offset:-4096
	v_bfe_u32 v46, v47, 16, 1
	v_add3_u32 v46, v47, v46, s45
	global_store_short_d16_hi v[50:51], v46, off offset:2048
	v_bfe_u32 v46, v48, 16, 1
	v_add3_u32 v46, v48, v46, s45
	global_store_short_d16_hi v[52:53], v46, off
	v_bfe_u32 v46, v49, 16, 1
	v_add3_u32 v46, v49, v46, s45
	global_store_short_d16_hi v[52:53], v46, off offset:2048
	v_bfe_u32 v46, v42, 16, 1
	v_add3_u32 v42, v42, v46, s45
	global_store_short_d16_hi v[50:51], v42, off offset:32
	v_bfe_u32 v42, v43, 16, 1
	v_add3_u32 v42, v43, v42, s45
	global_store_short_d16_hi v[50:51], v42, off offset:2080
	v_bfe_u32 v42, v44, 16, 1
	v_add3_u32 v42, v44, v42, s45
	global_store_short_d16_hi v[52:53], v42, off offset:32
	v_bfe_u32 v42, v45, 16, 1
	v_add3_u32 v42, v45, v42, s45
	global_store_short_d16_hi v[52:53], v42, off offset:2080
	v_bfe_u32 v42, v38, 16, 1
	s_mov_b32 s4, 0x58000
	v_add3_u32 v38, v38, v42, s45
	v_add_co_u32_e32 v42, vcc, s4, v130
	s_mov_b32 s4, 0x59000
	s_nop 0
	v_addc_co_u32_e32 v43, vcc, 0, v131, vcc
	v_add_co_u32_e32 v44, vcc, s4, v130
	s_nop 1
	v_addc_co_u32_e32 v45, vcc, 0, v131, vcc
	global_store_short_d16_hi v[44:45], v38, off offset:-4096
	v_bfe_u32 v38, v39, 16, 1
	v_add3_u32 v38, v39, v38, s45
	global_store_short_d16_hi v[42:43], v38, off offset:2048
	v_bfe_u32 v38, v40, 16, 1
	v_add3_u32 v38, v40, v38, s45
	global_store_short_d16_hi v[44:45], v38, off
	v_bfe_u32 v38, v41, 16, 1
	v_add3_u32 v38, v41, v38, s45
	global_store_short_d16_hi v[44:45], v38, off offset:2048
	v_bfe_u32 v38, v34, 16, 1
	v_add3_u32 v34, v34, v38, s45
	global_store_short_d16_hi v[42:43], v34, off offset:32
	v_bfe_u32 v34, v35, 16, 1
	v_add3_u32 v34, v35, v34, s45
	global_store_short_d16_hi v[42:43], v34, off offset:2080
	v_bfe_u32 v34, v36, 16, 1
	v_add3_u32 v34, v36, v34, s45
	global_store_short_d16_hi v[44:45], v34, off offset:32
	v_bfe_u32 v34, v37, 16, 1
	v_add3_u32 v34, v37, v34, s45
	global_store_short_d16_hi v[44:45], v34, off offset:2080
	v_bfe_u32 v34, v30, 16, 1
	v_add3_u32 v30, v30, v34, s45
	global_store_short_d16_hi v[66:67], v30, off offset:256
	v_bfe_u32 v30, v31, 16, 1
	v_add3_u32 v30, v31, v30, s45
	global_store_short_d16_hi v[66:67], v30, off offset:2304
	v_bfe_u32 v30, v32, 16, 1
	v_add3_u32 v30, v32, v30, s45
	global_store_short_d16_hi v[68:69], v30, off offset:256
	v_bfe_u32 v30, v33, 16, 1
	v_add3_u32 v30, v33, v30, s45
	global_store_short_d16_hi v[68:69], v30, off offset:2304
	v_bfe_u32 v30, v26, 16, 1
	v_add3_u32 v26, v26, v30, s45
; DI u16 f2bf(float x) { unsigned u = __float_as_uint(x); u += 0x7fffu + ((u >> 16) & 1u); return (u16)(u >> 16); }
; DI void phase_outproj(const Params& p, int layer, char* lds) {
;     ...
;   for (int u = bl; u < per_x; u += nbl) {
;     ...
;     u16* yo = (u16*)(p.ws + OFF_XB) + base;
; #pragma unroll
;     for (int ai = 0; ai < 2; ++ai)
; #pragma unroll
;       for (int bj = 0; bj < 2; ++bj)
; #pragma unroll
;         for (int m = 0; m < 4; ++m) {
; #pragma unroll
;           for (int n = 0; n < 2; ++n)
; #pragma unroll
;             for (int j = 0; j < 4; ++j) yo[(ai * 128 + m * 16 + j) * DM + bj * 128 + n * 16] = f2bf(acc[ai][bj][m][n][j]);
;           __builtin_amdgcn_sched_barrier(0);
;         }
;   }
	global_store_short_d16_hi v[66:67], v26, off offset:288
	v_bfe_u32 v26, v27, 16, 1
	v_add3_u32 v26, v27, v26, s45
	global_store_short_d16_hi v[66:67], v26, off offset:2336
	v_bfe_u32 v26, v28, 16, 1
	v_add3_u32 v26, v28, v26, s45
	global_store_short_d16_hi v[68:69], v26, off offset:288
	v_bfe_u32 v26, v29, 16, 1
	v_add3_u32 v26, v29, v26, s45
	global_store_short_d16_hi v[68:69], v26, off offset:2336
	v_bfe_u32 v26, v22, 16, 1
	v_add3_u32 v22, v22, v26, s45
	global_store_short_d16_hi v[58:59], v22, off offset:256
	v_bfe_u32 v22, v23, 16, 1
	v_add3_u32 v22, v23, v22, s45
	global_store_short_d16_hi v[58:59], v22, off offset:2304
	v_bfe_u32 v22, v24, 16, 1
	v_add3_u32 v22, v24, v22, s45
	global_store_short_d16_hi v[60:61], v22, off offset:256
	v_bfe_u32 v22, v25, 16, 1
	v_add3_u32 v22, v25, v22, s45
	global_store_short_d16_hi v[60:61], v22, off offset:2304
	v_bfe_u32 v22, v18, 16, 1
	v_add3_u32 v18, v18, v22, s45
	global_store_short_d16_hi v[58:59], v18, off offset:288
	v_bfe_u32 v18, v19, 16, 1
	v_add3_u32 v18, v19, v18, s45
	global_store_short_d16_hi v[58:59], v18, off offset:2336
	v_bfe_u32 v18, v20, 16, 1
	v_add3_u32 v18, v20, v18, s45
	global_store_short_d16_hi v[60:61], v18, off offset:288
	v_bfe_u32 v18, v21, 16, 1
	v_add3_u32 v18, v21, v18, s45
	global_store_short_d16_hi v[60:61], v18, off offset:2336
	v_bfe_u32 v18, v14, 16, 1
	v_add3_u32 v14, v14, v18, s45
	global_store_short_d16_hi v[50:51], v14, off offset:256
	v_bfe_u32 v14, v15, 16, 1
	v_add3_u32 v14, v15, v14, s45
	global_store_short_d16_hi v[50:51], v14, off offset:2304
	v_bfe_u32 v14, v16, 16, 1
	v_add3_u32 v14, v16, v14, s45
	global_store_short_d16_hi v[52:53], v14, off offset:256
	v_bfe_u32 v14, v17, 16, 1
	v_add3_u32 v14, v17, v14, s45
	global_store_short_d16_hi v[52:53], v14, off offset:2304
	v_bfe_u32 v14, v10, 16, 1
	v_add3_u32 v10, v10, v14, s45
	global_store_short_d16_hi v[50:51], v10, off offset:288
	v_bfe_u32 v10, v11, 16, 1
	v_add3_u32 v10, v11, v10, s45
	global_store_short_d16_hi v[50:51], v10, off offset:2336
	v_bfe_u32 v10, v12, 16, 1
	v_add3_u32 v10, v12, v10, s45
	global_store_short_d16_hi v[52:53], v10, off offset:288
	v_bfe_u32 v10, v13, 16, 1
	v_add3_u32 v10, v13, v10, s45
	global_store_short_d16_hi v[52:53], v10, off offset:2336
	v_bfe_u32 v10, v6, 16, 1
	v_add3_u32 v6, v6, v10, s45
	global_store_short_d16_hi v[42:43], v6, off offset:256
	v_bfe_u32 v6, v7, 16, 1
	v_add3_u32 v6, v7, v6, s45
	global_store_short_d16_hi v[42:43], v6, off offset:2304
	v_bfe_u32 v6, v8, 16, 1
	v_add3_u32 v6, v8, v6, s45
	global_store_short_d16_hi v[44:45], v6, off offset:256
	v_bfe_u32 v6, v9, 16, 1
	v_add3_u32 v6, v9, v6, s45
	global_store_short_d16_hi v[44:45], v6, off offset:2304
	v_bfe_u32 v6, v0, 16, 1
	v_add3_u32 v0, v0, v6, s45
	global_store_short_d16_hi v[42:43], v0, off offset:288
	v_bfe_u32 v0, v1, 16, 1
	v_add3_u32 v0, v1, v0, s45
	global_store_short_d16_hi v[42:43], v0, off offset:2336
	v_bfe_u32 v0, v2, 16, 1
	v_add3_u32 v0, v2, v0, s45
	global_store_short_d16_hi v[44:45], v0, off offset:288
	v_bfe_u32 v0, v3, 16, 1
	v_add3_u32 v0, v3, v0, s45
	global_store_short_d16_hi v[44:45], v0, off offset:2336
	s_add_i32 s23, s23, s63
	v_readlane_b32 s4, v254, 54
	s_cmp_lt_i32 s23, s4
	s_cbranch_scc0 .LBB0_528
; #define G8_WV(n) asm volatile("s_waitcnt vmcnt(" #n ")" ::: "memory")
; #define G8_BAR __builtin_amdgcn_s_barrier()
; DI void gemm8p(const u16* __restrict__ A, const u16* __restrict__ Bt, int brow, int bcol, f32x4 (&acc)[2][2][4][2]) {
;     ...
;   int tid8 = threadIdx.x; asm volatile("" : "+v"(tid8));
;   const int wid = tid8 >> 6, lane = tid8 & 63, wr = wid >> 2, wc = wid & 3, fr = lane & 15, fq = lane >> 4;
;   int soff0, soff1;
;   { int r_, c_; g8_stage_rc(tid8 * 16, r_, c_); soff0 = r_ * K + c_; g8_stage_rc(tid8 * 16 + 8192, r_, c_); soff1 = r_ * K + c_; }
;   bf16x8 At[4][2], B0[2][2], B1[2][2];
;   constexpr int nt = K / BK;
;   __syncthreads();
;   G8_STAGE(G8_SB(0, 0), Bt, bcol, 0); G8_STAGE(G8_SA(0, 0), A, brow, 0);
;   G8_STAGE(G8_SB(0, 1), Bt, bcol + HALF, 0); G8_STAGE(G8_SA(0, 1), A, brow + HALF, 0);
;   if (wr == 1) G8_BAR;
;   G8_WV(4); G8_BAR;
;   G8_STAGE(G8_SB(1, 0), Bt, bcol, 1); G8_STAGE(G8_SA(1, 0), A, brow, 1); G8_STAGE(G8_SB(1, 1), Bt, bcol + HALF, 1);
;   G8_WV(6); G8_BAR;
.LBB0_522:
	s_cmp_lg_u32 s32, 0
	s_cselect_b64 vcc, -1, 0
	v_mov_b32_e32 v143, v184
	s_ashr_i32 s4, s23, 31
	v_ashrrev_i32_e32 v0, 31, v143
	v_lshrrev_b32_e32 v0, 26, v0
	v_add_u32_e32 v0, v143, v0
	v_ashrrev_i32_e32 v14, 6, v0
	v_bfe_i32 v0, v143, 27, 1
	v_lshlrev_b32_e32 v23, 4, v143
	v_lshrrev_b32_e32 v0, 22, v0
	v_add_u32_e32 v0, v23, v0
	v_and_b32_e32 v0, 0xfffffc00, v0
	v_sub_u32_e32 v0, v23, v0
	v_lshrrev_b32_e32 v1, 4, v0
	v_bitop3_b32 v0, v1, v0, 32 bitop3:0x6c
	v_ashrrev_i32_e32 v2, 31, v0
	v_lshrrev_b32_e32 v2, 26, v2
	v_lshlrev_b32_e32 v1, 3, v14
	v_add_u32_e32 v2, v0, v2
	v_and_b32_e32 v1, 0x3ffff0, v1
	v_ashrrev_i32_e32 v16, 6, v2
	v_lshlrev_b32_e32 v3, 5, v14
	v_and_b32_e32 v2, 0xc0, v2
	v_add_u32_e32 v1, v16, v1
	v_and_b32_e32 v17, 32, v3
	v_sub_u32_e32 v0, v0, v2
	v_ashrrev_i16_sdwa v18, v185, sext(v0) dst_sel:DWORD dst_unused:UNUSED_PAD src0_sel:DWORD src1_sel:BYTE_0
	v_lshl_or_b32 v0, v1, 10, v17
	v_add_u32_e32 v1, 0x2000, v23
	v_ashrrev_i32_e32 v2, 31, v1
	v_lshrrev_b32_e32 v2, 22, v2
	v_add_u32_e32 v2, v1, v2
	v_ashrrev_i32_e32 v19, 10, v2
	s_lshr_b32 s4, s4, 30
	v_mul_i32_i24_e32 v2, 0x400, v19
	s_add_i32 s4, s23, s4
	v_sub_u32_e32 v1, v1, v2
	s_ashr_i32 s6, s4, 2
	s_and_b32 s4, s4, 0xfffffc
	v_lshrrev_b32_e32 v2, 4, v1
	s_sub_i32 s7, s23, s4
	s_lshl_b32 s4, s6, 3
	v_bitop3_b32 v1, v2, v1, 32 bitop3:0x6c
	s_or_b32 s8, s4, s28
	v_readlane_b32 s4, v254, 30
	v_ashrrev_i32_e32 v3, 31, v1
	v_readlane_b32 s5, v254, 31
	v_lshrrev_b32_e32 v3, 26, v3
	s_and_b64 s[4:5], s[4:5], exec
	v_lshlrev_b32_e32 v2, 3, v19
	v_add_u32_e32 v3, v1, v3
	s_cselect_b32 s4, s8, s6
	v_and_b32_e32 v2, 0x3ffff0, v2
	v_ashrrev_i32_e32 v20, 6, v3
	v_lshlrev_b32_e32 v6, 5, v19
	v_and_b32_e32 v3, 0xc0, v3
	s_lshl_b32 s6, s4, 8
	s_lshl_b32 s4, s7, 8
	v_add_u32_e32 v2, v20, v2
	v_and_b32_e32 v21, 32, v6
	v_sub_u32_e32 v1, v1, v3
	v_ashrrev_i16_sdwa v22, v185, sext(v1) dst_sel:DWORD dst_unused:UNUSED_PAD src0_sel:DWORD src1_sel:BYTE_0
	v_lshl_or_b32 v1, v2, 10, v21
	s_ashr_i32 s5, s4, 31
	v_add_u32_sdwa v0, v0, sext(v18) dst_sel:DWORD dst_unused:UNUSED_PAD src0_sel:DWORD src1_sel:WORD_0
	v_add_u32_sdwa v2, v1, sext(v22) dst_sel:DWORD dst_unused:UNUSED_PAD src0_sel:DWORD src1_sel:WORD_0
	s_lshl_b64 s[8:9], s[4:5], 11
	s_add_u32 s10, s20, s8
	v_ashrrev_i32_e32 v1, 31, v0
	v_ashrrev_i32_e32 v3, 31, v2
	s_addc_u32 s11, s21, s9
	v_lshlrev_b64 v[24:25], 1, v[0:1]
	v_lshlrev_b64 v[26:27], 1, v[2:3]
	s_ashr_i32 s7, s6, 31
	v_lshl_add_u64 v[0:1], s[10:11], 0, v[24:25]
	v_lshl_add_u64 v[2:3], s[10:11], 0, v[26:27]
	s_lshl_b64 s[10:11], s[6:7], 11
	v_readlane_b32 s24, v254, 49
	v_readlane_b32 s25, v254, 50
	s_add_u32 s12, s24, s10
	v_readlane_b32 s5, v255, 7
	s_addc_u32 s13, s25, s11
	v_lshl_add_u64 v[6:7], s[12:13], 0, v[24:25]
	v_add_u32_e32 v145, s5, v23
	v_lshl_add_u64 v[8:9], s[12:13], 0, v[26:27]
	s_or_b32 s12, s4, 0x80
	v_readfirstlane_b32 s5, v145
	v_add_u32_e32 v149, 0x2000, v145
	s_ashr_i32 s13, s12, 31
	s_mov_b32 m0, s5
	v_readfirstlane_b32 s5, v149
	v_add_u32_e32 v150, 0, v23
	s_lshl_b64 s[12:13], s[12:13], 11
	s_barrier
	s_cbranch_vccnz .Lopf_s0
	global_load_lds_dwordx4 v[0:1], off
.Lopf_s0:
	s_mov_b32 m0, s5
	v_readfirstlane_b32 s5, v150
	v_add_u32_e32 v151, 0x2000, v150
	s_add_u32 s12, s20, s12
	s_cbranch_vccnz .Lopf_s1
	global_load_lds_dwordx4 v[2:3], off
.Lopf_s1:
	s_mov_b32 m0, s5
	v_readfirstlane_b32 s5, v151
	s_addc_u32 s13, s21, s13
	s_cbranch_vccnz .Lopf_s2
	global_load_lds_dwordx4 v[6:7], off
.Lopf_s2:
	s_mov_b32 m0, s5
	v_lshl_add_u64 v[12:13], s[12:13], 0, v[24:25]
	v_readlane_b32 s5, v255, 8
	v_lshl_add_u64 v[10:11], s[12:13], 0, v[26:27]
	s_or_b32 s12, s6, 0x80
	v_add_u32_e32 v153, s5, v23
	s_ashr_i32 s13, s12, 31
	v_readfirstlane_b32 s5, v153
	v_add_u32_e32 v154, 0x2000, v153
	s_lshl_b64 s[12:13], s[12:13], 11
	s_cbranch_vccnz .Lopf_s3
	global_load_lds_dwordx4 v[8:9], off
.Lopf_s3:
	s_mov_b32 m0, s5
	v_readfirstlane_b32 s5, v154
	s_add_u32 s12, s24, s12
	v_add_u32_e32 v155, 0x4000, v150
	s_cbranch_vccnz .Lopf_s4
	global_load_lds_dwordx4 v[12:13], off
.Lopf_s4:
	s_mov_b32 m0, s5
	s_addc_u32 s13, s25, s13
	v_readfirstlane_b32 s5, v155
	v_add_u32_e32 v157, 0x6000, v150
	s_cbranch_vccnz .Lopf_s5
	global_load_lds_dwordx4 v[10:11], off
.Lopf_s5:
	v_lshl_add_u64 v[130:131], s[12:13], 0, v[24:25]
	s_mov_b32 m0, s5
	v_readfirstlane_b32 s5, v157
	s_cbranch_vccnz .Lopf_s6
	global_load_lds_dwordx4 v[130:131], off
.Lopf_s6:
	v_lshl_add_u64 v[132:133], s[12:13], 0, v[26:27]
	s_mov_b32 m0, s5
	v_ashrrev_i32_e32 v15, 8, v143
	s_cbranch_vccnz .Lopf_s7
	global_load_lds_dwordx4 v[132:133], off
.Lopf_s7:
	v_cmp_eq_u32_e32 vcc, 1, v15
	s_and_saveexec_b64 s[12:13], vcc
	s_cbranch_execz .LBB0_524
	s_barrier
.LBB0_524:
	s_or_b64 exec, exec, s[12:13]
	v_readlane_b32 s7, v255, 9
	s_mov_b64 s[24:25], 0x80
	v_lshl_add_u64 v[0:1], v[0:1], 0, s[24:25]
	v_add_u32_e32 v158, s7, v23
	v_add_u32_e32 v159, 0x2000, v158
	v_readfirstlane_b32 s5, v158
	s_mov_b32 m0, s5
	v_readfirstlane_b32 s5, v159
	v_add_u32_e32 v160, 0x8000, v150
	v_cmp_ne_u32_e64 vcc, s32, 0
	s_cbranch_vccnz .Lopf_w4h
	s_waitcnt vmcnt(4)
	s_branch .Lopf_w4d

; #define G8_WV(n) asm volatile("s_waitcnt vmcnt(" #n ")" ::: "memory")
; #define G8_BAR __builtin_amdgcn_s_barrier()
; DI void gemm8p(const u16* __restrict__ A, const u16* __restrict__ Bt, int brow, int bcol, f32x4 (&acc)[2][2][4][2]) {
;     ...
;   G8_STAGE(G8_SB(1, 0), Bt, bcol, 1); G8_STAGE(G8_SA(1, 0), A, brow, 1); G8_STAGE(G8_SB(1, 1), Bt, bcol + HALF, 1);
;   G8_WV(6); G8_BAR;
; DI void phase_outproj(const Params& p, int layer, char* lds) {
;     ...
;     f32x4 acc[2][2][4][2];
; #pragma unroll
;     for (int ai = 0; ai < 2; ++ai)
; #pragma unroll
;       for (int bj = 0; bj < 2; ++bj)
; #pragma unroll
;         for (int m = 0; m < 4; ++m)
; #pragma unroll
;           for (int n = 0; n < 2; ++n) acc[ai][bj][m][n] = (f32x4){0.f, 0.f, 0.f, 0.f};
.Lopf_w4d:
	s_barrier
	global_load_lds_dwordx4 v[0:1], off
	v_lshl_add_u64 v[0:1], v[2:3], 0, s[24:25]
	s_mov_b32 m0, s5
	v_readfirstlane_b32 s5, v160
	v_add_u32_e32 v161, 0xa000, v150
	v_readlane_b32 s12, v255, 10
	global_load_lds_dwordx4 v[0:1], off
	v_lshl_add_u64 v[0:1], v[6:7], 0, s[24:25]
	s_mov_b32 m0, s5
	v_readfirstlane_b32 s5, v161
	v_add_u32_e32 v162, s12, v23
	global_load_lds_dwordx4 v[0:1], off
	v_lshl_add_u64 v[0:1], v[8:9], 0, s[24:25]
	s_mov_b32 m0, s5
	v_readfirstlane_b32 s5, v162
	v_add_u32_e32 v163, 0x2000, v162
	global_load_lds_dwordx4 v[0:1], off
	v_lshl_add_u64 v[0:1], v[12:13], 0, s[24:25]
	s_mov_b32 m0, s5
	v_readfirstlane_b32 s5, v163
	global_load_lds_dwordx4 v[0:1], off
	v_lshl_add_u64 v[0:1], v[10:11], 0, s[24:25]
	s_mov_b32 m0, s5
	v_and_b32_e32 v24, 15, v143
	global_load_lds_dwordx4 v[0:1], off
	v_lshlrev_b32_e32 v1, 2, v143
	v_and_b32_e32 v25, 48, v143
	v_lshlrev_b32_e32 v0, 6, v24
	v_and_b32_e32 v1, 32, v1
	v_bitop3_b32 v0, v0, v1, v25 bitop3:0x36
	v_readlane_b32 s5, v255, 7
	v_lshlrev_b32_e32 v2, 6, v143
	v_add_u32_e32 v8, s7, v0
	v_add_u32_e32 v6, s5, v0
	v_readlane_b32 s5, v255, 8
	v_add_u32_e32 v9, s12, v0
	v_add_u32_e32 v12, 0, v0
	v_add_u32_e32 v7, s5, v0
	s_movk_i32 s5, 0x3c0
	v_and_or_b32 v0, v2, s5, v25
	v_xad_u32 v13, v0, v1, 0
	v_lshlrev_b32_e32 v0, 13, v14
	v_and_b32_e32 v10, 0x3000, v2
	v_and_b32_e32 v0, 0xffffc000, v0
	v_lshlrev_b32_e32 v2, 13, v19
	v_lshl_add_u32 v0, v16, 10, v0
	v_and_b32_e32 v2, 0xffffc000, v2
	v_or_b32_e32 v0, v0, v17
	v_lshl_add_u32 v2, v20, 10, v2
	v_readlane_b32 s12, v255, 18
	v_add_u32_sdwa v0, v0, sext(v18) dst_sel:DWORD dst_unused:UNUSED_PAD src0_sel:DWORD src1_sel:WORD_0
	v_or_b32_e32 v2, v2, v21
	v_readlane_b32 s13, v255, 19
	s_add_u32 s8, s12, s8
	v_ashrrev_i32_e32 v1, 31, v0
	v_add_u32_sdwa v2, v2, sext(v22) dst_sel:DWORD dst_unused:UNUSED_PAD src0_sel:DWORD src1_sel:WORD_0
	v_cmp_ne_u32_e64 vcc, s32, 0
	s_cbranch_vccnz .Lopf_w6
	s_waitcnt vmcnt(6)
.Lopf_w6:
	v_lshlrev_b32_e32 v11, 13, v15
	s_addc_u32 s9, s13, s9
	v_lshlrev_b64 v[0:1], 1, v[0:1]
	v_ashrrev_i32_e32 v3, 31, v2
	v_or_b32_e32 v15, 0x800, v11
	v_or_b32_e32 v23, 0x1000, v11
	v_or_b32_e32 v24, 0x1800, v11
	v_lshl_add_u64 v[134:135], s[8:9], 0, v[0:1]
	v_lshlrev_b64 v[2:3], 1, v[2:3]
	v_lshl_add_u64 v[138:139], s[10:11], 0, v[0:1]
	v_mov_b32_e32 v0, 0
	v_lshl_add_u64 v[136:137], s[8:9], 0, v[2:3]
	v_lshl_add_u64 v[140:141], s[10:11], 0, v[2:3]
	s_mov_b32 s5, -2
	v_add_u32_e32 v165, v6, v10
	v_add_u32_e32 v148, v12, v11
	v_add_u32_e32 v147, v13, v15
	v_add_u32_e32 v146, v13, v23
	v_add_u32_e32 v144, v13, v24
	v_add_u32_e32 v164, v7, v10
	v_add_u32_e32 v156, v8, v10
	v_add_u32_e32 v152, v9, v10
	v_mov_b32_e32 v1, v0
	v_mov_b32_e32 v2, v0
	v_mov_b32_e32 v3, v0
	v_mov_b32_e32 v6, v0
	v_mov_b32_e32 v7, v0
	v_mov_b32_e32 v8, v0
	v_mov_b32_e32 v9, v0
	v_mov_b32_e32 v10, v0
	v_mov_b32_e32 v11, v0
	v_mov_b32_e32 v12, v0
	v_mov_b32_e32 v13, v0
	v_mov_b32_e32 v14, v0
	v_mov_b32_e32 v15, v0
	v_mov_b32_e32 v16, v0
	v_mov_b32_e32 v17, v0
	v_mov_b32_e32 v18, v0
	v_mov_b32_e32 v19, v0
	v_mov_b32_e32 v20, v0
	v_mov_b32_e32 v21, v0
	v_mov_b32_e32 v22, v0
	v_mov_b32_e32 v23, v0
	v_mov_b32_e32 v24, v0
	v_mov_b32_e32 v25, v0
	v_mov_b32_e32 v26, v0
	v_mov_b32_e32 v27, v0
	v_mov_b32_e32 v28, v0
	v_mov_b32_e32 v29, v0
	v_mov_b32_e32 v30, v0
	v_mov_b32_e32 v31, v0
	v_mov_b32_e32 v32, v0
	v_mov_b32_e32 v33, v0
	v_mov_b32_e32 v34, v0
	v_mov_b32_e32 v35, v0
	v_mov_b32_e32 v36, v0
	v_mov_b32_e32 v37, v0
	v_mov_b32_e32 v38, v0
	v_mov_b32_e32 v39, v0
	v_mov_b32_e32 v40, v0
	v_mov_b32_e32 v41, v0
	v_mov_b32_e32 v42, v0
	v_mov_b32_e32 v43, v0
	v_mov_b32_e32 v44, v0
	v_mov_b32_e32 v45, v0
	v_mov_b32_e32 v46, v0
	v_mov_b32_e32 v47, v0
	v_mov_b32_e32 v48, v0
	v_mov_b32_e32 v49, v0
	v_mov_b32_e32 v50, v0
	v_mov_b32_e32 v51, v0
	v_mov_b32_e32 v52, v0
	v_mov_b32_e32 v53, v0
	v_mov_b32_e32 v54, v0
	v_mov_b32_e32 v55, v0
	v_mov_b32_e32 v56, v0
	v_mov_b32_e32 v57, v0
	v_mov_b32_e32 v58, v0
	v_mov_b32_e32 v59, v0
	v_mov_b32_e32 v60, v0
	v_mov_b32_e32 v61, v0
	v_mov_b32_e32 v62, v0
	v_mov_b32_e32 v63, v0
	v_mov_b32_e32 v64, v0
	v_mov_b32_e32 v65, v0
	v_mov_b32_e32 v66, v0
	v_mov_b32_e32 v67, v0
	v_mov_b32_e32 v68, v0
	v_mov_b32_e32 v69, v0
	v_mov_b32_e32 v70, v0
	v_mov_b32_e32 v71, v0
	v_mov_b32_e32 v72, v0
	v_mov_b32_e32 v73, v0
	v_mov_b32_e32 v74, v0
	v_mov_b32_e32 v75, v0
	v_mov_b32_e32 v76, v0
	v_mov_b32_e32 v77, v0
	v_mov_b32_e32 v78, v0
	v_mov_b32_e32 v79, v0
	v_mov_b32_e32 v80, v0
	v_mov_b32_e32 v81, v0
	v_mov_b32_e32 v82, v0
	v_mov_b32_e32 v83, v0
	v_mov_b32_e32 v84, v0
	v_mov_b32_e32 v85, v0
	v_mov_b32_e32 v86, v0
	v_mov_b32_e32 v87, v0
	v_mov_b32_e32 v88, v0
	v_mov_b32_e32 v89, v0
	v_mov_b32_e32 v90, v0
	v_mov_b32_e32 v91, v0
	v_mov_b32_e32 v92, v0
	v_mov_b32_e32 v93, v0
	v_mov_b32_e32 v94, v0
	v_mov_b32_e32 v95, v0
	v_mov_b32_e32 v96, v0
	v_mov_b32_e32 v97, v0
	v_mov_b32_e32 v98, v0
	v_mov_b32_e32 v99, v0
	v_mov_b32_e32 v100, v0
	v_mov_b32_e32 v101, v0
	v_mov_b32_e32 v102, v0
	v_mov_b32_e32 v103, v0
	v_mov_b32_e32 v104, v0
	v_mov_b32_e32 v105, v0
	v_mov_b32_e32 v106, v0
	v_mov_b32_e32 v107, v0
	v_mov_b32_e32 v108, v0
	v_mov_b32_e32 v109, v0
	v_mov_b32_e32 v110, v0
	v_mov_b32_e32 v111, v0
	v_mov_b32_e32 v112, v0
	v_mov_b32_e32 v113, v0
	v_mov_b32_e32 v114, v0
	v_mov_b32_e32 v115, v0
	v_mov_b32_e32 v116, v0
	v_mov_b32_e32 v117, v0
	v_mov_b32_e32 v118, v0
	v_mov_b32_e32 v119, v0
	v_mov_b32_e32 v120, v0
	v_mov_b32_e32 v121, v0
	v_mov_b32_e32 v122, v0
	v_mov_b32_e32 v123, v0
	v_mov_b32_e32 v124, v0
	v_mov_b32_e32 v125, v0
	v_mov_b32_e32 v126, v0
	v_mov_b32_e32 v127, v0
	v_mov_b32_e32 v128, v0
	v_mov_b32_e32 v129, v0
	s_barrier
